# in-proj K-loop: scalar address and counter arithmetic moved from loader sections into gaps between MFMAs
# baseline (speedup 1.0000x reference)
.LBB0_137:
	s_ashr_i32 s49, s48, 31
	s_lshl_b64 s[22:23], s[48:49], 20
	s_add_u32 s52, s26, s22
	s_addc_u32 s53, s27, s23
	s_and_b64 s[0:1], s[0:1], exec
	s_cselect_b32 s22, s53, s7
	s_cselect_b32 s23, s52, s6
	s_add_u32 s0, s12, 0x80080
	s_addc_u32 s1, s13, 0
	s_add_u32 s38, s6, 0x100
	v_mov_b32_e32 v2, 0
	s_addc_u32 s39, s7, 0
	s_mov_b32 s49, -2
	v_mov_b32_e32 v3, v2
	v_mov_b32_e32 v4, v2
	v_mov_b32_e32 v5, v2
	v_mov_b32_e32 v6, v2
	v_mov_b32_e32 v7, v2
	v_mov_b32_e32 v8, v2
	v_mov_b32_e32 v9, v2
	v_mov_b32_e32 v14, v2
	v_mov_b32_e32 v15, v2
	v_mov_b32_e32 v16, v2
	v_mov_b32_e32 v17, v2
	v_mov_b32_e32 v22, v2
	v_mov_b32_e32 v23, v2
	v_mov_b32_e32 v24, v2
	v_mov_b32_e32 v25, v2
	v_mov_b32_e32 v30, v2
	v_mov_b32_e32 v31, v2
	v_mov_b32_e32 v32, v2
	v_mov_b32_e32 v33, v2
	v_mov_b32_e32 v38, v2
	v_mov_b32_e32 v39, v2
	v_mov_b32_e32 v40, v2
	v_mov_b32_e32 v41, v2
	v_mov_b32_e32 v46, v2
	v_mov_b32_e32 v47, v2
	v_mov_b32_e32 v48, v2
	v_mov_b32_e32 v49, v2
	v_mov_b32_e32 v54, v2
	v_mov_b32_e32 v55, v2
	v_mov_b32_e32 v56, v2
	v_mov_b32_e32 v57, v2
	v_mov_b32_e32 v10, v2
	v_mov_b32_e32 v11, v2
	v_mov_b32_e32 v12, v2
	v_mov_b32_e32 v13, v2
	v_mov_b32_e32 v18, v2
	v_mov_b32_e32 v19, v2
	v_mov_b32_e32 v20, v2
	v_mov_b32_e32 v21, v2
	v_mov_b32_e32 v26, v2
	v_mov_b32_e32 v27, v2
	v_mov_b32_e32 v28, v2
	v_mov_b32_e32 v29, v2
	v_mov_b32_e32 v34, v2
	v_mov_b32_e32 v35, v2
	v_mov_b32_e32 v36, v2
	v_mov_b32_e32 v37, v2
	v_mov_b32_e32 v42, v2
	v_mov_b32_e32 v43, v2
	v_mov_b32_e32 v44, v2
	v_mov_b32_e32 v45, v2
	v_mov_b32_e32 v50, v2
	v_mov_b32_e32 v51, v2
	v_mov_b32_e32 v52, v2
	v_mov_b32_e32 v53, v2
	v_mov_b32_e32 v58, v2
	v_mov_b32_e32 v59, v2
	v_mov_b32_e32 v60, v2
	v_mov_b32_e32 v61, v2
	v_mov_b32_e32 v62, v2
	v_mov_b32_e32 v63, v2
	v_mov_b32_e32 v64, v2
	v_mov_b32_e32 v65, v2
	v_mov_b32_e32 v66, v2
	v_mov_b32_e32 v67, v2
	v_mov_b32_e32 v68, v2
	v_mov_b32_e32 v69, v2
	v_mov_b32_e32 v70, v2
	v_mov_b32_e32 v71, v2
	v_mov_b32_e32 v72, v2
	v_mov_b32_e32 v73, v2
	v_mov_b32_e32 v78, v2
	v_mov_b32_e32 v79, v2
	v_mov_b32_e32 v80, v2
	v_mov_b32_e32 v81, v2
	v_mov_b32_e32 v86, v2
	v_mov_b32_e32 v87, v2
	v_mov_b32_e32 v88, v2
	v_mov_b32_e32 v89, v2
	v_mov_b32_e32 v94, v2
	v_mov_b32_e32 v95, v2
	v_mov_b32_e32 v96, v2
	v_mov_b32_e32 v97, v2
	v_mov_b32_e32 v102, v2
	v_mov_b32_e32 v103, v2
	v_mov_b32_e32 v104, v2
	v_mov_b32_e32 v105, v2
	v_mov_b32_e32 v110, v2
	v_mov_b32_e32 v111, v2
	v_mov_b32_e32 v112, v2
	v_mov_b32_e32 v113, v2
	v_mov_b32_e32 v118, v2
	v_mov_b32_e32 v119, v2
	v_mov_b32_e32 v120, v2
	v_mov_b32_e32 v121, v2
	v_mov_b32_e32 v74, v2
	v_mov_b32_e32 v75, v2
	v_mov_b32_e32 v76, v2
	v_mov_b32_e32 v77, v2
	v_mov_b32_e32 v82, v2
	v_mov_b32_e32 v83, v2
	v_mov_b32_e32 v84, v2
	v_mov_b32_e32 v85, v2
	v_mov_b32_e32 v90, v2
	v_mov_b32_e32 v91, v2
	v_mov_b32_e32 v92, v2
	v_mov_b32_e32 v93, v2
	v_mov_b32_e32 v98, v2
	v_mov_b32_e32 v99, v2
	v_mov_b32_e32 v100, v2
	v_mov_b32_e32 v101, v2
	v_mov_b32_e32 v106, v2
	v_mov_b32_e32 v107, v2
	v_mov_b32_e32 v108, v2
	v_mov_b32_e32 v109, v2
	v_mov_b32_e32 v114, v2
	v_mov_b32_e32 v115, v2
	v_mov_b32_e32 v116, v2
	v_mov_b32_e32 v117, v2
	v_mov_b32_e32 v122, v2
	v_mov_b32_e32 v123, v2
	v_mov_b32_e32 v124, v2
	v_mov_b32_e32 v125, v2
	v_mov_b32_e32 v126, v2
	v_mov_b32_e32 v127, v2
	v_mov_b32_e32 v128, v2
	v_mov_b32_e32 v129, v2
	v_add_u32_e32 v224, 0x10000, v149
	v_add_u32_e32 v225, 0x14000, v149
	v_add_u32_e32 v226, 0x18000, v149
	v_add_u32_e32 v227, 0x1c000, v149
	s_add_u32 s6, s0, 0xfff80080
	s_addc_u32 s7, s1, -1
	s_add_i32 s76, 0, 0x10000
	s_cmp_eq_u32 s49, 28
	s_cselect_b32 s13, s51, s7
	s_cselect_b32 s12, s50, s6
	s_cselect_b32 s7, s22, s39
	s_cselect_b32 s6, s23, s38
.LBB0_138:
	ds_read_b128 v[130:133], v224
	ds_read_b128 v[134:137], v224 offset:1024
	ds_read_b128 v[138:141], v224 offset:2048
	ds_read_b128 v[142:145], v224 offset:3072
	s_add_i32 m0, s31, 0xc000
	ds_read_b128 v[152:155], v174
	ds_read_b128 v[166:169], v174 offset:1024
	ds_read_b128 v[170:173], v174 offset:2048
	ds_read_b128 v[176:179], v174 offset:3072
	ds_read_b128 v[180:183], v174 offset:4096
	ds_read_b128 v[184:187], v174 offset:5120
	ds_read_b128 v[188:191], v174 offset:6144
	global_load_lds_dwordx4 v162, s[0:1]
	s_add_i32 m0, s31, 0xe000
	ds_read_b128 v[192:195], v174 offset:7168
	global_load_lds_dwordx4 v164, s[0:1]
	s_waitcnt lgkmcnt(8)
	s_barrier
	s_setprio 1
	s_waitcnt lgkmcnt(7)
	v_mfma_f32_16x16x32_bf16 v[126:129], v[130:133], v[152:155], v[126:129]
	v_mfma_f32_16x16x32_bf16 v[122:125], v[138:141], v[152:155], v[122:125]
	s_add_i32 s78, 0, 0x14000
	s_waitcnt lgkmcnt(5)
	v_mfma_f32_16x16x32_bf16 v[114:117], v[130:133], v[170:173], v[114:117]
	s_add_i32 s76, s76, s30
	v_mfma_f32_16x16x32_bf16 v[106:109], v[138:141], v[170:173], v[106:109]
	s_waitcnt lgkmcnt(3)
	v_mfma_f32_16x16x32_bf16 v[98:101], v[130:133], v[180:183], v[98:101]
	v_mfma_f32_16x16x32_bf16 v[90:93], v[138:141], v[180:183], v[90:93]
	s_waitcnt lgkmcnt(1)
	v_mfma_f32_16x16x32_bf16 v[82:85], v[130:133], v[188:191], v[82:85]
	v_mfma_f32_16x16x32_bf16 v[74:77], v[138:141], v[188:191], v[74:77]
	v_mfma_f32_16x16x32_bf16 v[126:129], v[134:137], v[166:169], v[126:129]
	v_mfma_f32_16x16x32_bf16 v[122:125], v[142:145], v[166:169], v[122:125]
	v_mfma_f32_16x16x32_bf16 v[114:117], v[134:137], v[176:179], v[114:117]
	v_mfma_f32_16x16x32_bf16 v[106:109], v[142:145], v[176:179], v[106:109]
	v_mfma_f32_16x16x32_bf16 v[98:101], v[134:137], v[184:187], v[98:101]
	v_mfma_f32_16x16x32_bf16 v[90:93], v[142:145], v[184:187], v[90:93]
	s_waitcnt lgkmcnt(0)
	v_mfma_f32_16x16x32_bf16 v[82:85], v[134:137], v[192:195], v[82:85]
	v_mfma_f32_16x16x32_bf16 v[74:77], v[142:145], v[192:195], v[74:77]
	s_setprio 0
	s_barrier
	s_mov_b32 m0, s76
	ds_read_b128 v[196:199], v225
	ds_read_b128 v[200:203], v225 offset:1024
	ds_read_b128 v[204:207], v225 offset:2048
	global_load_lds_dwordx4 v158, s[6:7]
	s_add_i32 m0, s76, 0x2000
	ds_read_b128 v[216:219], v225 offset:3072
	global_load_lds_dwordx4 v146, s[6:7]
	s_barrier
	s_setprio 1
	s_waitcnt lgkmcnt(3)
	v_mfma_f32_16x16x32_bf16 v[118:121], v[196:199], v[152:155], v[118:121]
	s_waitcnt lgkmcnt(1)
	v_mfma_f32_16x16x32_bf16 v[110:113], v[204:207], v[152:155], v[110:113]
	s_mov_b32 m0, s31
	v_mfma_f32_16x16x32_bf16 v[102:105], v[196:199], v[170:173], v[102:105]
	s_add_u32 s98, s12, 0x80
	s_addc_u32 s99, s13, 0
	v_mfma_f32_16x16x32_bf16 v[94:97], v[204:207], v[170:173], v[94:97]
	v_mfma_f32_16x16x32_bf16 v[86:89], v[196:199], v[180:183], v[86:89]
	v_mfma_f32_16x16x32_bf16 v[78:81], v[204:207], v[180:183], v[78:81]
	v_mfma_f32_16x16x32_bf16 v[70:73], v[196:199], v[188:191], v[70:73]
	v_mfma_f32_16x16x32_bf16 v[66:69], v[204:207], v[188:191], v[66:69]
	v_mfma_f32_16x16x32_bf16 v[118:121], v[200:203], v[166:169], v[118:121]
	s_waitcnt lgkmcnt(0)
	v_mfma_f32_16x16x32_bf16 v[110:113], v[216:219], v[166:169], v[110:113]
	v_mfma_f32_16x16x32_bf16 v[102:105], v[200:203], v[176:179], v[102:105]
	v_mfma_f32_16x16x32_bf16 v[94:97], v[216:219], v[176:179], v[94:97]
	v_mfma_f32_16x16x32_bf16 v[86:89], v[200:203], v[184:187], v[86:89]
	v_mfma_f32_16x16x32_bf16 v[78:81], v[216:219], v[184:187], v[78:81]
	v_mfma_f32_16x16x32_bf16 v[70:73], v[200:203], v[192:195], v[70:73]
	v_mfma_f32_16x16x32_bf16 v[66:69], v[216:219], v[192:195], v[66:69]
	s_setprio 0
	s_barrier
	ds_read_b128 v[152:155], v174 offset:16384
	ds_read_b128 v[166:169], v174 offset:17408
	ds_read_b128 v[170:173], v174 offset:18432
	ds_read_b128 v[176:179], v174 offset:19456
	ds_read_b128 v[180:183], v174 offset:20480
	ds_read_b128 v[184:187], v174 offset:21504
	ds_read_b128 v[188:191], v174 offset:22528
	global_load_lds_dwordx4 v160, s[12:13]
	s_mov_b32 m0, s40
	ds_read_b128 v[192:195], v174 offset:23552
	global_load_lds_dwordx4 v156, s[12:13]
	s_barrier
	s_setprio 1
	s_waitcnt lgkmcnt(7)
	v_mfma_f32_16x16x32_bf16 v[62:65], v[130:133], v[152:155], v[62:65]
	v_mfma_f32_16x16x32_bf16 v[58:61], v[138:141], v[152:155], v[58:61]
	s_add_i32 s78, s78, s30
	s_waitcnt lgkmcnt(5)
	v_mfma_f32_16x16x32_bf16 v[50:53], v[130:133], v[170:173], v[50:53]
	v_mfma_f32_16x16x32_bf16 v[42:45], v[138:141], v[170:173], v[42:45]
	s_waitcnt lgkmcnt(3)
	v_mfma_f32_16x16x32_bf16 v[34:37], v[130:133], v[180:183], v[34:37]
	v_mfma_f32_16x16x32_bf16 v[26:29], v[138:141], v[180:183], v[26:29]
	s_waitcnt lgkmcnt(1)
	v_mfma_f32_16x16x32_bf16 v[18:21], v[130:133], v[188:191], v[18:21]
	v_mfma_f32_16x16x32_bf16 v[10:13], v[138:141], v[188:191], v[10:13]
	v_mfma_f32_16x16x32_bf16 v[62:65], v[134:137], v[166:169], v[62:65]
	v_mfma_f32_16x16x32_bf16 v[58:61], v[142:145], v[166:169], v[58:61]
	v_mfma_f32_16x16x32_bf16 v[50:53], v[134:137], v[176:179], v[50:53]
	v_mfma_f32_16x16x32_bf16 v[42:45], v[142:145], v[176:179], v[42:45]
	v_mfma_f32_16x16x32_bf16 v[34:37], v[134:137], v[184:187], v[34:37]
	v_mfma_f32_16x16x32_bf16 v[26:29], v[142:145], v[184:187], v[26:29]
	s_waitcnt lgkmcnt(0)
	v_mfma_f32_16x16x32_bf16 v[18:21], v[134:137], v[192:195], v[18:21]
	v_mfma_f32_16x16x32_bf16 v[10:13], v[142:145], v[192:195], v[10:13]
	s_setprio 0
	s_barrier
	s_mov_b32 m0, s78
	s_add_u32 s76, s6, 0x80000
	s_addc_u32 s77, s7, 0
	global_load_lds_dwordx4 v158, s[76:77]
	s_add_i32 m0, s78, 0x2000
	s_nop 0
	global_load_lds_dwordx4 v146, s[76:77]
	s_waitcnt vmcnt(6)
	s_barrier
	s_setprio 1
	v_mfma_f32_16x16x32_bf16 v[54:57], v[196:199], v[152:155], v[54:57]
	v_mfma_f32_16x16x32_bf16 v[46:49], v[204:207], v[152:155], v[46:49]
	s_add_i32 s76, 0, 0x18000
	v_mfma_f32_16x16x32_bf16 v[38:41], v[196:199], v[170:173], v[38:41]
	s_add_u32 s12, s12, 0x80000
	s_addc_u32 s13, s13, 0
	v_mfma_f32_16x16x32_bf16 v[30:33], v[204:207], v[170:173], v[30:33]
	v_mfma_f32_16x16x32_bf16 v[22:25], v[196:199], v[180:183], v[22:25]
	v_mfma_f32_16x16x32_bf16 v[14:17], v[204:207], v[180:183], v[14:17]
	v_mfma_f32_16x16x32_bf16 v[6:9], v[196:199], v[188:191], v[6:9]
	v_mfma_f32_16x16x32_bf16 v[2:5], v[204:207], v[188:191], v[2:5]
	v_mfma_f32_16x16x32_bf16 v[54:57], v[200:203], v[166:169], v[54:57]
	v_mfma_f32_16x16x32_bf16 v[46:49], v[216:219], v[166:169], v[46:49]
	v_mfma_f32_16x16x32_bf16 v[38:41], v[200:203], v[176:179], v[38:41]
	v_mfma_f32_16x16x32_bf16 v[30:33], v[216:219], v[176:179], v[30:33]
	v_mfma_f32_16x16x32_bf16 v[22:25], v[200:203], v[184:187], v[22:25]
	v_mfma_f32_16x16x32_bf16 v[14:17], v[216:219], v[184:187], v[14:17]
	v_mfma_f32_16x16x32_bf16 v[6:9], v[200:203], v[192:195], v[6:9]
	v_mfma_f32_16x16x32_bf16 v[2:5], v[216:219], v[192:195], v[2:5]
	s_setprio 0
	s_barrier
	ds_read_b128 v[130:133], v226
	ds_read_b128 v[134:137], v226 offset:1024
	ds_read_b128 v[138:141], v226 offset:2048
	ds_read_b128 v[142:145], v226 offset:3072
	s_mov_b32 m0, s41
	ds_read_b128 v[152:155], v174 offset:32768
	ds_read_b128 v[166:169], v174 offset:33792
	ds_read_b128 v[170:173], v174 offset:34816
	ds_read_b128 v[176:179], v174 offset:35840
	ds_read_b128 v[180:183], v174 offset:36864
	ds_read_b128 v[184:187], v174 offset:37888
	ds_read_b128 v[188:191], v174 offset:38912
	global_load_lds_dwordx4 v160, s[12:13]
	s_mov_b32 m0, s60
	ds_read_b128 v[192:195], v174 offset:39936
	global_load_lds_dwordx4 v156, s[12:13]
	s_waitcnt lgkmcnt(8)
	s_barrier
	s_setprio 1
	s_waitcnt lgkmcnt(7)
	v_mfma_f32_16x16x32_bf16 v[126:129], v[130:133], v[152:155], v[126:129]
	v_mfma_f32_16x16x32_bf16 v[122:125], v[138:141], v[152:155], v[122:125]
	s_add_i32 s12, 0, 0x1c000
	s_waitcnt lgkmcnt(5)
	v_mfma_f32_16x16x32_bf16 v[114:117], v[130:133], v[170:173], v[114:117]
	s_add_i32 s13, s76, s30
	v_mfma_f32_16x16x32_bf16 v[106:109], v[138:141], v[170:173], v[106:109]
	s_add_u32 s100, s6, 0x80
	s_addc_u32 s101, s7, 0
	s_waitcnt lgkmcnt(3)
	v_mfma_f32_16x16x32_bf16 v[98:101], v[130:133], v[180:183], v[98:101]
	v_mfma_f32_16x16x32_bf16 v[90:93], v[138:141], v[180:183], v[90:93]
	s_waitcnt lgkmcnt(1)
	v_mfma_f32_16x16x32_bf16 v[82:85], v[130:133], v[188:191], v[82:85]
	v_mfma_f32_16x16x32_bf16 v[74:77], v[138:141], v[188:191], v[74:77]
	v_mfma_f32_16x16x32_bf16 v[126:129], v[134:137], v[166:169], v[126:129]
	v_mfma_f32_16x16x32_bf16 v[122:125], v[142:145], v[166:169], v[122:125]
	v_mfma_f32_16x16x32_bf16 v[114:117], v[134:137], v[176:179], v[114:117]
	v_mfma_f32_16x16x32_bf16 v[106:109], v[142:145], v[176:179], v[106:109]
	v_mfma_f32_16x16x32_bf16 v[98:101], v[134:137], v[184:187], v[98:101]
	v_mfma_f32_16x16x32_bf16 v[90:93], v[142:145], v[184:187], v[90:93]
	s_waitcnt lgkmcnt(0)
	v_mfma_f32_16x16x32_bf16 v[82:85], v[134:137], v[192:195], v[82:85]
	v_mfma_f32_16x16x32_bf16 v[74:77], v[142:145], v[192:195], v[74:77]
	s_setprio 0
	s_barrier
	s_mov_b32 m0, s13
	ds_read_b128 v[196:199], v227
	ds_read_b128 v[200:203], v227 offset:1024
	ds_read_b128 v[204:207], v227 offset:2048
	global_load_lds_dwordx4 v158, s[100:101]
	s_add_i32 m0, s13, 0x2000
	ds_read_b128 v[216:219], v227 offset:3072
	global_load_lds_dwordx4 v146, s[100:101]
	s_barrier
	s_setprio 1
	s_waitcnt lgkmcnt(3)
	v_mfma_f32_16x16x32_bf16 v[118:121], v[196:199], v[152:155], v[118:121]
	s_waitcnt lgkmcnt(1)
	v_mfma_f32_16x16x32_bf16 v[110:113], v[204:207], v[152:155], v[110:113]
	s_mov_b32 m0, s64
	v_mfma_f32_16x16x32_bf16 v[102:105], v[196:199], v[170:173], v[102:105]
	v_mfma_f32_16x16x32_bf16 v[94:97], v[204:207], v[170:173], v[94:97]
	v_mfma_f32_16x16x32_bf16 v[86:89], v[196:199], v[180:183], v[86:89]
	v_mfma_f32_16x16x32_bf16 v[78:81], v[204:207], v[180:183], v[78:81]
	v_mfma_f32_16x16x32_bf16 v[70:73], v[196:199], v[188:191], v[70:73]
	v_mfma_f32_16x16x32_bf16 v[66:69], v[204:207], v[188:191], v[66:69]
	v_mfma_f32_16x16x32_bf16 v[118:121], v[200:203], v[166:169], v[118:121]
	s_waitcnt lgkmcnt(0)
	v_mfma_f32_16x16x32_bf16 v[110:113], v[216:219], v[166:169], v[110:113]
	v_mfma_f32_16x16x32_bf16 v[102:105], v[200:203], v[176:179], v[102:105]
	v_mfma_f32_16x16x32_bf16 v[94:97], v[216:219], v[176:179], v[94:97]
	v_mfma_f32_16x16x32_bf16 v[86:89], v[200:203], v[184:187], v[86:89]
	v_mfma_f32_16x16x32_bf16 v[78:81], v[216:219], v[184:187], v[78:81]
	v_mfma_f32_16x16x32_bf16 v[70:73], v[200:203], v[192:195], v[70:73]
	v_mfma_f32_16x16x32_bf16 v[66:69], v[216:219], v[192:195], v[66:69]
	s_setprio 0
	s_barrier
	ds_read_b128 v[152:155], v174 offset:49152
	ds_read_b128 v[166:169], v174 offset:50176
	ds_read_b128 v[170:173], v174 offset:51200
	ds_read_b128 v[176:179], v174 offset:52224
	ds_read_b128 v[180:183], v174 offset:53248
	ds_read_b128 v[184:187], v174 offset:54272
	ds_read_b128 v[188:191], v174 offset:55296
	global_load_lds_dwordx4 v160, s[98:99]
	s_mov_b32 m0, s65
	ds_read_b128 v[192:195], v174 offset:56320
	global_load_lds_dwordx4 v156, s[98:99]
	s_barrier
	s_setprio 1
	s_waitcnt lgkmcnt(7)
	v_mfma_f32_16x16x32_bf16 v[62:65], v[130:133], v[152:155], v[62:65]
	v_mfma_f32_16x16x32_bf16 v[58:61], v[138:141], v[152:155], v[58:61]
	s_add_i32 s12, s12, s30
	s_waitcnt lgkmcnt(5)
	v_mfma_f32_16x16x32_bf16 v[50:53], v[130:133], v[170:173], v[50:53]
	v_mfma_f32_16x16x32_bf16 v[42:45], v[138:141], v[170:173], v[42:45]
	s_waitcnt lgkmcnt(3)
	v_mfma_f32_16x16x32_bf16 v[34:37], v[130:133], v[180:183], v[34:37]
	v_mfma_f32_16x16x32_bf16 v[26:29], v[138:141], v[180:183], v[26:29]
	s_waitcnt lgkmcnt(1)
	v_mfma_f32_16x16x32_bf16 v[18:21], v[130:133], v[188:191], v[18:21]
	v_mfma_f32_16x16x32_bf16 v[10:13], v[138:141], v[188:191], v[10:13]
	v_mfma_f32_16x16x32_bf16 v[62:65], v[134:137], v[166:169], v[62:65]
	v_mfma_f32_16x16x32_bf16 v[58:61], v[142:145], v[166:169], v[58:61]
	v_mfma_f32_16x16x32_bf16 v[50:53], v[134:137], v[176:179], v[50:53]
	v_mfma_f32_16x16x32_bf16 v[42:45], v[142:145], v[176:179], v[42:45]
	v_mfma_f32_16x16x32_bf16 v[34:37], v[134:137], v[184:187], v[34:37]
	v_mfma_f32_16x16x32_bf16 v[26:29], v[142:145], v[184:187], v[26:29]
	s_waitcnt lgkmcnt(0)
	v_mfma_f32_16x16x32_bf16 v[18:21], v[134:137], v[192:195], v[18:21]
	v_mfma_f32_16x16x32_bf16 v[10:13], v[142:145], v[192:195], v[10:13]
	s_setprio 0
	s_barrier
	s_mov_b32 m0, s12
	s_add_u32 s6, s6, 0x80080
	s_addc_u32 s7, s7, 0
	global_load_lds_dwordx4 v158, s[6:7]
	s_add_i32 m0, s12, 0x2000
	s_nop 0
	global_load_lds_dwordx4 v146, s[6:7]
	s_waitcnt vmcnt(6)
	s_barrier
	s_setprio 1
	v_mfma_f32_16x16x32_bf16 v[54:57], v[196:199], v[152:155], v[54:57]
	v_mfma_f32_16x16x32_bf16 v[46:49], v[204:207], v[152:155], v[46:49]
	s_add_i32 s49, s49, 2
	v_mfma_f32_16x16x32_bf16 v[38:41], v[196:199], v[170:173], v[38:41]
	s_add_u32 s0, s0, 0x100
	s_addc_u32 s1, s1, 0
	v_mfma_f32_16x16x32_bf16 v[30:33], v[204:207], v[170:173], v[30:33]
	s_add_u32 s38, s38, 0x100
	s_addc_u32 s39, s39, 0
	v_mfma_f32_16x16x32_bf16 v[22:25], v[196:199], v[180:183], v[22:25]
	s_add_u32 s6, s0, 0xfff80080
	s_addc_u32 s7, s1, -1
	v_mfma_f32_16x16x32_bf16 v[14:17], v[204:207], v[180:183], v[14:17]
	s_add_i32 s76, 0, 0x10000
	v_mfma_f32_16x16x32_bf16 v[6:9], v[196:199], v[188:191], v[6:9]
	s_cmp_eq_u32 s49, 28
	s_cselect_b32 s13, s51, s7
	s_cselect_b32 s12, s50, s6
	s_cselect_b32 s7, s22, s39
	s_cselect_b32 s6, s23, s38
	v_mfma_f32_16x16x32_bf16 v[2:5], v[204:207], v[188:191], v[2:5]
	v_mfma_f32_16x16x32_bf16 v[54:57], v[200:203], v[166:169], v[54:57]
	v_mfma_f32_16x16x32_bf16 v[46:49], v[216:219], v[166:169], v[46:49]
	v_mfma_f32_16x16x32_bf16 v[38:41], v[200:203], v[176:179], v[38:41]
	v_mfma_f32_16x16x32_bf16 v[30:33], v[216:219], v[176:179], v[30:33]
	v_mfma_f32_16x16x32_bf16 v[22:25], v[200:203], v[184:187], v[22:25]
	v_mfma_f32_16x16x32_bf16 v[14:17], v[216:219], v[184:187], v[14:17]
	v_mfma_f32_16x16x32_bf16 v[6:9], v[200:203], v[192:195], v[6:9]
	v_mfma_f32_16x16x32_bf16 v[2:5], v[216:219], v[192:195], v[2:5]
	s_setprio 0
	s_cmp_gt_u32 s49, 29
	s_barrier
	s_cbranch_scc0 .LBB0_138
	v_mov_b32_e32 v0, v148
	s_cmp_gt_i32 s69, 15
	v_and_b32_e32 v176, 15, v0
	v_bfe_u32 v175, v0, 4, 2
	s_mov_b64 s[0:1], -1
	s_cbranch_scc0 .LBB0_157
	s_cmp_gt_u32 s69, 23
	s_cbranch_scc0 .LBB0_154
	s_cmp_gt_u32 s69, 31
	s_cbranch_scc0 .LBB0_151
	s_cmp_gt_u32 s69, 39
	s_cbranch_scc0 .LBB0_148
	v_mul_f32_e32 v0, 0xbfb8aa3b, v126
	v_exp_f32_e32 v131, v0
	s_lshr_b32 s0, s75, 3
	s_mulk_i32 s0, 0x880
	s_lshl_b32 s1, s75, 8
	v_add_f32_e32 v131, 1.0, v131
	v_rcp_f32_e32 v132, v131
	v_mul_f32_e32 v131, 0xbfb8aa3b, v122
	v_mul_f32_e32 v133, 0xbfb8aa3b, v127
	v_mul_f32_e32 v134, 0xbfb8aa3b, v123
	v_mul_f32_e32 v135, 0xbfb8aa3b, v128
	v_mul_f32_e32 v136, 0xbfb8aa3b, v124
	v_mul_f32_e32 v137, 0xbfb8aa3b, v129
	v_mul_f32_e32 v138, 0xbfb8aa3b, v125
	v_mul_f32_e32 v139, 0xbfb8aa3b, v118
	v_mul_f32_e32 v140, 0xbfb8aa3b, v110
	v_mul_f32_e32 v141, 0xbfb8aa3b, v119
	v_mul_f32_e32 v142, 0xbfb8aa3b, v111
	v_mul_f32_e32 v143, 0xbfb8aa3b, v120
	v_mul_f32_e32 v152, 0xbfb8aa3b, v112
	v_mul_f32_e32 v153, 0xbfb8aa3b, v121
	v_mul_f32_e32 v154, 0xbfb8aa3b, v113
	v_mul_f32_e32 v155, 0xbfb8aa3b, v114
	v_mul_f32_e32 v177, 0xbfb8aa3b, v106
	v_mul_f32_e32 v178, 0xbfb8aa3b, v115
	v_mul_f32_e32 v179, 0xbfb8aa3b, v107
	v_mul_f32_e32 v180, 0xbfb8aa3b, v116
	v_mul_f32_e32 v181, 0xbfb8aa3b, v108
	v_mul_f32_e32 v182, 0xbfb8aa3b, v117
	v_mul_f32_e32 v183, 0xbfb8aa3b, v109
	v_mul_f32_e32 v184, 0xbfb8aa3b, v102
	v_mul_f32_e32 v185, 0xbfb8aa3b, v94
	v_mul_f32_e32 v186, 0xbfb8aa3b, v103
	v_mul_f32_e32 v187, 0xbfb8aa3b, v95
	v_mul_f32_e32 v188, 0xbfb8aa3b, v104
	v_mul_f32_e32 v189, 0xbfb8aa3b, v96
	v_mul_f32_e32 v190, 0xbfb8aa3b, v105
	v_mul_f32_e32 v191, 0xbfb8aa3b, v97
	v_mul_f32_e32 v192, 0xbfb8aa3b, v98
	v_mul_f32_e32 v193, 0xbfb8aa3b, v90
	v_mul_f32_e32 v194, 0xbfb8aa3b, v99
	v_mul_f32_e32 v195, 0xbfb8aa3b, v91
	v_mul_f32_e32 v196, 0xbfb8aa3b, v100
	v_mul_f32_e32 v197, 0xbfb8aa3b, v92
	v_mul_f32_e32 v198, 0xbfb8aa3b, v101
	v_mul_f32_e32 v199, 0xbfb8aa3b, v93
	v_mul_f32_e32 v200, 0xbfb8aa3b, v86
	v_mul_f32_e32 v201, 0xbfb8aa3b, v78
	v_mul_f32_e32 v202, 0xbfb8aa3b, v87
	v_mul_f32_e32 v203, 0xbfb8aa3b, v79
	v_mul_f32_e32 v204, 0xbfb8aa3b, v88
	v_mul_f32_e32 v205, 0xbfb8aa3b, v80
	v_mul_f32_e32 v206, 0xbfb8aa3b, v89
	v_mul_f32_e32 v207, 0xbfb8aa3b, v81
	v_mul_f32_e32 v208, 0xbfb8aa3b, v82
	v_mul_f32_e32 v209, 0xbfb8aa3b, v74
	v_mul_f32_e32 v215, 0xbfb8aa3b, v83
	v_mul_f32_e32 v216, 0xbfb8aa3b, v75
	v_mul_f32_e32 v217, 0xbfb8aa3b, v84
	v_mul_f32_e32 v218, 0xbfb8aa3b, v76
	v_mul_f32_e32 v219, 0xbfb8aa3b, v85
	v_mul_f32_e32 v220, 0xbfb8aa3b, v77
	v_mul_f32_e32 v221, 0xbfb8aa3b, v70
	v_mul_f32_e32 v222, 0xbfb8aa3b, v66
	v_mul_f32_e32 v223, 0xbfb8aa3b, v71
	v_mul_f32_e32 v224, 0xbfb8aa3b, v67
	v_mul_f32_e32 v225, 0xbfb8aa3b, v72
	v_mul_f32_e32 v226, 0xbfb8aa3b, v68
	v_mul_f32_e32 v227, 0xbfb8aa3b, v73
	v_mul_f32_e32 v228, 0xbfb8aa3b, v69
	v_mul_f32_e32 v229, 0xbfb8aa3b, v62
	v_mul_f32_e32 v230, 0xbfb8aa3b, v58
	v_mul_f32_e32 v231, 0xbfb8aa3b, v63
	v_mul_f32_e32 v232, 0xbfb8aa3b, v59
	v_mul_f32_e32 v233, 0xbfb8aa3b, v64
	v_mul_f32_e32 v234, 0xbfb8aa3b, v60
	v_mul_f32_e32 v235, 0xbfb8aa3b, v65
	v_mul_f32_e32 v236, 0xbfb8aa3b, v61
	v_mul_f32_e32 v237, 0xbfb8aa3b, v54
	v_mul_f32_e32 v238, 0xbfb8aa3b, v46
	v_mul_f32_e32 v239, 0xbfb8aa3b, v55
	s_and_b32 s1, s1, 0x700
	s_add_i32 s0, s0, s66
	v_exp_f32_e32 v173, v131
	v_exp_f32_e32 v133, v133
	v_exp_f32_e32 v172, v134
	v_exp_f32_e32 v171, v135
	v_exp_f32_e32 v170, v136
	v_exp_f32_e32 v169, v137
	v_exp_f32_e32 v131, v138
	v_exp_f32_e32 v168, v139
	v_exp_f32_e32 v167, v140
	v_exp_f32_e32 v166, v141
	v_exp_f32_e32 v145, v142
	v_exp_f32_e32 v144, v143
	v_exp_f32_e32 v143, v152
	v_exp_f32_e32 v142, v153
	v_exp_f32_e32 v141, v154
	v_exp_f32_e32 v140, v155
	v_exp_f32_e32 v139, v177
	v_exp_f32_e32 v138, v178
	v_exp_f32_e32 v213, v179
	v_exp_f32_e32 v155, v180
	v_exp_f32_e32 v154, v181
	v_exp_f32_e32 v153, v182
	v_exp_f32_e32 v152, v183
	v_exp_f32_e32 v212, v184
	v_exp_f32_e32 v211, v185
	v_exp_f32_e32 v252, v186
	v_exp_f32_e32 v251, v187
	v_exp_f32_e32 v250, v188
	v_exp_f32_e32 v249, v189
	v_exp_f32_e32 v248, v190
	v_exp_f32_e32 v247, v191
	v_exp_f32_e32 v246, v192
	v_exp_f32_e32 v245, v193
	v_exp_f32_e32 v244, v194
	v_exp_f32_e32 v243, v195
	v_exp_f32_e32 v242, v196
	v_exp_f32_e32 v241, v197
	v_exp_f32_e32 v184, v198
	v_exp_f32_e32 v177, v199
	v_exp_f32_e32 v198, v200
	v_exp_f32_e32 v199, v201
	v_exp_f32_e32 v197, v202
	v_exp_f32_e32 v196, v203
	v_exp_f32_e32 v195, v204
	v_exp_f32_e32 v194, v205
	v_exp_f32_e32 v193, v206
	v_exp_f32_e32 v192, v207
	v_exp_f32_e32 v191, v208
	v_exp_f32_e32 v190, v209
	v_exp_f32_e32 v189, v215
	v_exp_f32_e32 v188, v216
	v_exp_f32_e32 v187, v217
	v_exp_f32_e32 v186, v218
	v_exp_f32_e32 v185, v219
	v_exp_f32_e32 v201, v220
	v_exp_f32_e32 v200, v221
	v_exp_f32_e32 v221, v222
	v_exp_f32_e32 v220, v223
	v_exp_f32_e32 v219, v224
	v_exp_f32_e32 v218, v225
	v_exp_f32_e32 v217, v226
	v_exp_f32_e32 v216, v227
	v_exp_f32_e32 v215, v228
	v_exp_f32_e32 v209, v229
	v_exp_f32_e32 v208, v230
	v_exp_f32_e32 v207, v231
	v_exp_f32_e32 v206, v232
	v_exp_f32_e32 v205, v233
	v_exp_f32_e32 v204, v234
	v_exp_f32_e32 v203, v235
	v_exp_f32_e32 v202, v236
	v_exp_f32_e32 v223, v237
	v_exp_f32_e32 v222, v238
	v_exp_f32_e32 v238, v239
	s_add_i32 s0, s0, s1
	s_lshl_b32 s1, s69, 8
	v_lshl_or_b32 v130, v175, 3, s1
	s_cmp_gt_u32 s69, 47
	v_or_b32_e32 v240, s0, v176
	v_or_b32_e32 v130, s61, v130
	s_mov_b64 s[0:1], -1
	v_mul_f32_e32 v237, 0xbfb8aa3b, v47
	v_mul_f32_e32 v236, 0xbfb8aa3b, v56
	v_mul_f32_e32 v235, 0xbfb8aa3b, v48
	v_mul_f32_e32 v234, 0xbfb8aa3b, v57
	v_mul_f32_e32 v233, 0xbfb8aa3b, v49
	v_mul_f32_e32 v232, 0xbfb8aa3b, v50
	v_mul_f32_e32 v231, 0xbfb8aa3b, v42
	v_mul_f32_e32 v230, 0xbfb8aa3b, v51
	v_mul_f32_e32 v229, 0xbfb8aa3b, v43
	v_mul_f32_e32 v228, 0xbfb8aa3b, v18
	s_cbranch_scc0 .LBB0_145
	v_add_f32_e32 v178, 1.0, v171
	v_rcp_f32_e32 v179, v178
	v_add_f32_e32 v178, 1.0, v170
	v_add_f32_e32 v134, 1.0, v173
	v_add_f32_e32 v135, 1.0, v133
	v_add_f32_e32 v137, 1.0, v172
	v_rcp_f32_e32 v181, v178
	v_add_f32_e32 v178, 1.0, v169
	v_rcp_f32_e32 v134, v134
	v_rcp_f32_e32 v135, v135
	v_rcp_f32_e32 v137, v137
	v_rcp_f32_e32 v180, v178
	v_add_f32_e32 v178, 1.0, v131
	v_rcp_f32_e32 v182, v178
	v_mov_b32_e32 v0, v240
	v_mov_b32_e32 v136, v130
	v_cvt_pk_bf16_f32 v178, v132, v135
	v_cvt_pk_bf16_f32 v179, v179, v180
	v_cvt_pk_bf16_f32 v180, v134, v137
	v_mov_b64_e32 v[134:135], s[8:9]
	v_ashrrev_i32_e32 v137, 31, v136
	v_cvt_pk_bf16_f32 v181, v181, v182
	v_mad_i64_i32 v[182:183], s[0:1], v0, s47, v[134:135]
	v_lshlrev_b64 v[136:137], 1, v[136:137]
	v_lshl_add_u64 v[182:183], v[182:183], 0, v[136:137]
	global_store_dwordx4 v[182:183], v[178:181], off
	s_nop 1
	v_add_f32_e32 v179, 1.0, v167
	v_add_f32_e32 v178, 1.0, v168
	v_rcp_f32_e32 v180, v179
	v_add_f32_e32 v179, 1.0, v166
	v_add_f32_e32 v181, 1.0, v145
	v_add_f32_e32 v239, 1.0, v144
	v_add_f32_e32 v224, 1.0, v143
	v_add_f32_e32 v225, 1.0, v142
	v_add_f32_e32 v226, 1.0, v141
	v_rcp_f32_e32 v178, v178
	v_rcp_f32_e32 v179, v179
	v_rcp_f32_e32 v181, v181
	v_rcp_f32_e32 v239, v239
	v_rcp_f32_e32 v224, v224
	v_rcp_f32_e32 v225, v225
	v_rcp_f32_e32 v226, v226
	v_cvt_pk_bf16_f32 v178, v178, v179
	v_cvt_pk_bf16_f32 v180, v180, v181
	v_cvt_pk_bf16_f32 v179, v239, v225
	v_cvt_pk_bf16_f32 v181, v224, v226
	global_store_dwordx4 v[182:183], v[178:181], off offset:256
	s_nop 1
	v_add_f32_e32 v179, 1.0, v139
	v_add_f32_e32 v178, 1.0, v140
	v_rcp_f32_e32 v180, v179
	v_add_f32_e32 v179, 1.0, v138
	v_add_f32_e32 v183, 1.0, v155
	v_add_f32_e32 v225, 1.0, v153
	v_rcp_f32_e32 v178, v178
	v_rcp_f32_e32 v179, v179
	v_add_f32_e32 v181, 1.0, v213
	v_rcp_f32_e32 v183, v183
	v_add_f32_e32 v224, 1.0, v154
	v_rcp_f32_e32 v225, v225
	v_add_f32_e32 v226, 1.0, v152
	v_rcp_f32_e32 v181, v181
	v_rcp_f32_e32 v224, v224
	v_rcp_f32_e32 v226, v226
	v_add_u32_e32 v182, 16, v0
	v_cvt_pk_bf16_f32 v178, v178, v179
	v_cvt_pk_bf16_f32 v179, v183, v225
	v_mad_i64_i32 v[182:183], s[0:1], v182, s47, v[134:135]
	v_cvt_pk_bf16_f32 v180, v180, v181
	v_cvt_pk_bf16_f32 v181, v224, v226
	v_lshl_add_u64 v[182:183], v[182:183], 0, v[136:137]
	global_store_dwordx4 v[182:183], v[178:181], off
	s_nop 1
	v_add_f32_e32 v179, 1.0, v211
	v_add_f32_e32 v178, 1.0, v212
	v_rcp_f32_e32 v180, v179
	v_add_f32_e32 v179, 1.0, v252
	v_add_f32_e32 v181, 1.0, v251
	v_add_f32_e32 v224, 1.0, v250
	v_add_f32_e32 v225, 1.0, v249
	v_add_f32_e32 v226, 1.0, v248
	v_add_f32_e32 v239, 1.0, v247
	v_rcp_f32_e32 v178, v178
	v_rcp_f32_e32 v179, v179
	v_rcp_f32_e32 v181, v181
	v_rcp_f32_e32 v224, v224
	v_rcp_f32_e32 v225, v225
	v_rcp_f32_e32 v226, v226
	v_rcp_f32_e32 v239, v239
	v_cvt_pk_bf16_f32 v178, v178, v179
	v_cvt_pk_bf16_f32 v180, v180, v181
	v_cvt_pk_bf16_f32 v179, v224, v226
	v_cvt_pk_bf16_f32 v181, v225, v239
	global_store_dwordx4 v[182:183], v[178:181], off offset:256
	s_nop 1
	v_add_f32_e32 v179, 1.0, v245
	v_add_f32_e32 v178, 1.0, v246
	v_rcp_f32_e32 v180, v179
	v_add_f32_e32 v179, 1.0, v244
	v_add_f32_e32 v183, 1.0, v242
	v_add_f32_e32 v225, 1.0, v184
	v_rcp_f32_e32 v178, v178
	v_rcp_f32_e32 v179, v179
	v_add_f32_e32 v181, 1.0, v243
	v_rcp_f32_e32 v183, v183
	v_add_f32_e32 v224, 1.0, v241
	v_rcp_f32_e32 v225, v225
	v_add_f32_e32 v226, 1.0, v177
	v_rcp_f32_e32 v181, v181
	v_rcp_f32_e32 v224, v224
	v_rcp_f32_e32 v226, v226
	v_add_u32_e32 v182, 32, v0
	v_cvt_pk_bf16_f32 v178, v178, v179
	v_cvt_pk_bf16_f32 v179, v183, v225
	v_mad_i64_i32 v[182:183], s[0:1], v182, s47, v[134:135]
	v_cvt_pk_bf16_f32 v180, v180, v181
	v_cvt_pk_bf16_f32 v181, v224, v226
	v_lshl_add_u64 v[182:183], v[182:183], 0, v[136:137]
	global_store_dwordx4 v[182:183], v[178:181], off
	s_nop 1
	v_add_f32_e32 v179, 1.0, v199
	v_add_f32_e32 v178, 1.0, v198
	v_rcp_f32_e32 v180, v179
	v_add_f32_e32 v179, 1.0, v197
	v_add_f32_e32 v181, 1.0, v196
	v_add_f32_e32 v224, 1.0, v195
	v_add_f32_e32 v225, 1.0, v194
	v_add_f32_e32 v226, 1.0, v193
	v_add_f32_e32 v239, 1.0, v192
	v_rcp_f32_e32 v178, v178
	v_rcp_f32_e32 v179, v179
	v_rcp_f32_e32 v181, v181
	v_rcp_f32_e32 v224, v224
	v_rcp_f32_e32 v225, v225
	v_rcp_f32_e32 v226, v226
	v_rcp_f32_e32 v239, v239
	v_cvt_pk_bf16_f32 v178, v178, v179
	v_cvt_pk_bf16_f32 v180, v180, v181
	v_cvt_pk_bf16_f32 v179, v224, v226
	v_cvt_pk_bf16_f32 v181, v225, v239
	global_store_dwordx4 v[182:183], v[178:181], off offset:256
	s_nop 1
	v_add_f32_e32 v179, 1.0, v190
	v_add_f32_e32 v178, 1.0, v191
	v_rcp_f32_e32 v180, v179
	v_add_f32_e32 v179, 1.0, v189
	v_add_f32_e32 v183, 1.0, v187
	v_add_f32_e32 v225, 1.0, v185
	v_rcp_f32_e32 v178, v178
	v_rcp_f32_e32 v179, v179
	v_add_f32_e32 v181, 1.0, v188
	v_rcp_f32_e32 v183, v183
	v_add_f32_e32 v224, 1.0, v186
	v_rcp_f32_e32 v225, v225
	v_add_f32_e32 v226, 1.0, v201
	v_rcp_f32_e32 v181, v181
	v_rcp_f32_e32 v224, v224
	v_rcp_f32_e32 v226, v226
	v_add_u32_e32 v182, 48, v0
	v_cvt_pk_bf16_f32 v178, v178, v179
	v_cvt_pk_bf16_f32 v179, v183, v225
	v_mad_i64_i32 v[182:183], s[0:1], v182, s47, v[134:135]
	v_cvt_pk_bf16_f32 v180, v180, v181
	v_cvt_pk_bf16_f32 v181, v224, v226
	v_lshl_add_u64 v[182:183], v[182:183], 0, v[136:137]
	global_store_dwordx4 v[182:183], v[178:181], off
	s_nop 1
	v_add_f32_e32 v179, 1.0, v221
	v_add_f32_e32 v178, 1.0, v200
	v_rcp_f32_e32 v180, v179
	v_add_f32_e32 v179, 1.0, v220
	v_add_f32_e32 v181, 1.0, v219
	v_add_f32_e32 v224, 1.0, v218
	v_add_f32_e32 v225, 1.0, v217
	v_add_f32_e32 v226, 1.0, v216
	v_add_f32_e32 v239, 1.0, v215
	v_rcp_f32_e32 v178, v178
	v_rcp_f32_e32 v179, v179
	v_rcp_f32_e32 v181, v181
	v_rcp_f32_e32 v224, v224
	v_rcp_f32_e32 v225, v225
	v_rcp_f32_e32 v226, v226
	v_rcp_f32_e32 v239, v239
	v_cvt_pk_bf16_f32 v178, v178, v179
	v_cvt_pk_bf16_f32 v180, v180, v181
	v_cvt_pk_bf16_f32 v179, v224, v226
	v_cvt_pk_bf16_f32 v181, v225, v239
	global_store_dwordx4 v[182:183], v[178:181], off offset:256
	s_nop 1
	v_add_f32_e32 v179, 1.0, v208
	v_add_f32_e32 v178, 1.0, v209
	v_rcp_f32_e32 v180, v179
	v_add_f32_e32 v179, 1.0, v207
	v_add_f32_e32 v183, 1.0, v205
	v_add_f32_e32 v225, 1.0, v203
	v_rcp_f32_e32 v178, v178
	v_rcp_f32_e32 v179, v179
	v_add_f32_e32 v181, 1.0, v206
	v_rcp_f32_e32 v183, v183
	v_add_f32_e32 v224, 1.0, v204
	v_rcp_f32_e32 v225, v225
	v_add_f32_e32 v226, 1.0, v202
	v_rcp_f32_e32 v181, v181
	v_rcp_f32_e32 v224, v224
	v_rcp_f32_e32 v226, v226
	v_add_u32_e32 v182, 0x80, v0
	v_cvt_pk_bf16_f32 v178, v178, v179
	v_cvt_pk_bf16_f32 v179, v183, v225
	v_mad_i64_i32 v[182:183], s[0:1], v182, s47, v[134:135]
	v_cvt_pk_bf16_f32 v180, v180, v181
	v_cvt_pk_bf16_f32 v181, v224, v226
	v_lshl_add_u64 v[182:183], v[182:183], 0, v[136:137]
	global_store_dwordx4 v[182:183], v[178:181], off
	s_nop 1
	v_add_f32_e32 v179, 1.0, v222
	v_rcp_f32_e32 v180, v179
	v_exp_f32_e32 v179, v237
	v_exp_f32_e32 v224, v236
	v_exp_f32_e32 v226, v234
	v_exp_f32_e32 v239, v233
	v_add_f32_e32 v179, 1.0, v179
	v_rcp_f32_e32 v225, v179
	v_exp_f32_e32 v179, v235
	v_add_f32_e32 v178, 1.0, v223
	v_add_f32_e32 v181, 1.0, v238
	v_add_f32_e32 v224, 1.0, v224
	v_add_f32_e32 v179, 1.0, v179
	v_rcp_f32_e32 v227, v179
	v_add_f32_e32 v179, 1.0, v226
	v_add_f32_e32 v226, 1.0, v239
	v_rcp_f32_e32 v178, v178
	v_rcp_f32_e32 v181, v181
	v_rcp_f32_e32 v224, v224
	v_rcp_f32_e32 v179, v179
	v_rcp_f32_e32 v226, v226
	v_cvt_pk_bf16_f32 v178, v178, v181
	v_cvt_pk_bf16_f32 v180, v180, v225
	v_cvt_pk_bf16_f32 v179, v224, v179
	v_cvt_pk_bf16_f32 v181, v227, v226
	global_store_dwordx4 v[182:183], v[178:181], off offset:256
	s_nop 1
	v_exp_f32_e32 v179, v231
	v_mul_f32_e32 v183, 0xbfb8aa3b, v52
	v_mul_f32_e32 v225, 0xbfb8aa3b, v53
	v_exp_f32_e32 v183, v183
	v_add_f32_e32 v179, 1.0, v179
	v_rcp_f32_e32 v181, v179
	v_exp_f32_e32 v179, v229
	v_exp_f32_e32 v225, v225
	v_mul_f32_e32 v226, 0xbfb8aa3b, v45
	v_exp_f32_e32 v178, v232
	v_add_f32_e32 v179, 1.0, v179
	v_rcp_f32_e32 v224, v179
	v_mul_f32_e32 v179, 0xbfb8aa3b, v44
	v_exp_f32_e32 v179, v179
	v_exp_f32_e32 v180, v230
	v_exp_f32_e32 v226, v226
	v_add_f32_e32 v183, 1.0, v183
	v_add_f32_e32 v179, 1.0, v179
	v_rcp_f32_e32 v227, v179
	v_add_f32_e32 v179, 1.0, v225
	v_add_f32_e32 v178, 1.0, v178
	v_add_f32_e32 v180, 1.0, v180
	v_rcp_f32_e32 v183, v183
	v_rcp_f32_e32 v179, v179
	v_add_f32_e32 v225, 1.0, v226
	v_rcp_f32_e32 v178, v178
	v_rcp_f32_e32 v180, v180
	v_rcp_f32_e32 v225, v225
	v_add_u32_e32 v182, 0x90, v0
	v_cvt_pk_bf16_f32 v179, v183, v179
	v_mad_i64_i32 v[182:183], s[0:1], v182, s47, v[134:135]
	v_cvt_pk_bf16_f32 v178, v178, v180
	v_cvt_pk_bf16_f32 v180, v181, v224
	v_cvt_pk_bf16_f32 v181, v227, v225
	v_lshl_add_u64 v[182:183], v[182:183], 0, v[136:137]
	global_store_dwordx4 v[182:183], v[178:181], off
	s_nop 1
	v_mul_f32_e32 v179, 0xbfb8aa3b, v30
	v_exp_f32_e32 v179, v179
	v_mul_f32_e32 v178, 0xbfb8aa3b, v38
	v_mul_f32_e32 v180, 0xbfb8aa3b, v39
	v_mul_f32_e32 v224, 0xbfb8aa3b, v40
	v_add_f32_e32 v179, 1.0, v179
	v_rcp_f32_e32 v181, v179
	v_mul_f32_e32 v179, 0xbfb8aa3b, v31
	v_exp_f32_e32 v179, v179
	v_mul_f32_e32 v226, 0xbfb8aa3b, v41
	v_mul_f32_e32 v227, 0xbfb8aa3b, v33
	v_exp_f32_e32 v178, v178
	v_add_f32_e32 v179, 1.0, v179
	v_rcp_f32_e32 v225, v179
	v_mul_f32_e32 v179, 0xbfb8aa3b, v32
	v_exp_f32_e32 v179, v179
	v_exp_f32_e32 v180, v180
	v_exp_f32_e32 v224, v224
	v_exp_f32_e32 v226, v226
	v_exp_f32_e32 v227, v227
	v_add_f32_e32 v179, 1.0, v179
	v_add_f32_e32 v178, 1.0, v178
	v_add_f32_e32 v180, 1.0, v180
	v_add_f32_e32 v224, 1.0, v224
	v_rcp_f32_e32 v239, v179
	v_add_f32_e32 v179, 1.0, v226
	v_add_f32_e32 v226, 1.0, v227
	v_rcp_f32_e32 v178, v178
	v_rcp_f32_e32 v180, v180
	v_rcp_f32_e32 v224, v224
	v_rcp_f32_e32 v179, v179
	v_rcp_f32_e32 v226, v226
	v_cvt_pk_bf16_f32 v178, v178, v180
	v_cvt_pk_bf16_f32 v180, v181, v225
	v_cvt_pk_bf16_f32 v179, v224, v179
	v_cvt_pk_bf16_f32 v181, v239, v226
	global_store_dwordx4 v[182:183], v[178:181], off offset:256
	s_nop 1
	v_mul_f32_e32 v179, 0xbfb8aa3b, v26
	v_exp_f32_e32 v179, v179
	v_mul_f32_e32 v183, 0xbfb8aa3b, v36
	v_mul_f32_e32 v225, 0xbfb8aa3b, v37
	v_mul_f32_e32 v178, 0xbfb8aa3b, v34
	v_add_f32_e32 v179, 1.0, v179
	v_rcp_f32_e32 v181, v179
	v_mul_f32_e32 v179, 0xbfb8aa3b, v27
	v_exp_f32_e32 v179, v179
	v_mul_f32_e32 v180, 0xbfb8aa3b, v35
	v_exp_f32_e32 v183, v183
	v_exp_f32_e32 v225, v225
	v_add_f32_e32 v179, 1.0, v179
	v_rcp_f32_e32 v224, v179
	v_mul_f32_e32 v179, 0xbfb8aa3b, v28
	v_exp_f32_e32 v179, v179
	v_mul_f32_e32 v226, 0xbfb8aa3b, v29
	v_exp_f32_e32 v178, v178
	v_exp_f32_e32 v180, v180
	v_exp_f32_e32 v226, v226
	v_add_f32_e32 v179, 1.0, v179
	v_add_f32_e32 v183, 1.0, v183
	v_rcp_f32_e32 v227, v179
	v_add_f32_e32 v179, 1.0, v225
	v_add_f32_e32 v178, 1.0, v178
	v_add_f32_e32 v180, 1.0, v180
	v_rcp_f32_e32 v183, v183
	v_rcp_f32_e32 v179, v179
	v_add_f32_e32 v225, 1.0, v226
	v_rcp_f32_e32 v178, v178
	v_rcp_f32_e32 v180, v180
	v_rcp_f32_e32 v225, v225
	v_add_u32_e32 v182, 0xa0, v0
	v_cvt_pk_bf16_f32 v179, v183, v179
	v_mad_i64_i32 v[182:183], s[0:1], v182, s47, v[134:135]
	v_cvt_pk_bf16_f32 v178, v178, v180
	v_cvt_pk_bf16_f32 v180, v181, v224
	v_cvt_pk_bf16_f32 v181, v227, v225
	v_lshl_add_u64 v[182:183], v[182:183], 0, v[136:137]
	global_store_dwordx4 v[182:183], v[178:181], off
	s_nop 1
	v_mul_f32_e32 v179, 0xbfb8aa3b, v14
	v_exp_f32_e32 v179, v179
	v_mul_f32_e32 v178, 0xbfb8aa3b, v22
	v_mul_f32_e32 v180, 0xbfb8aa3b, v23
	v_mul_f32_e32 v224, 0xbfb8aa3b, v24
	v_add_f32_e32 v179, 1.0, v179
	v_rcp_f32_e32 v181, v179
	v_mul_f32_e32 v179, 0xbfb8aa3b, v15
	v_exp_f32_e32 v179, v179
	v_mul_f32_e32 v226, 0xbfb8aa3b, v25
	v_mul_f32_e32 v227, 0xbfb8aa3b, v17
	v_exp_f32_e32 v178, v178
	v_add_f32_e32 v179, 1.0, v179
	v_rcp_f32_e32 v225, v179
	v_mul_f32_e32 v179, 0xbfb8aa3b, v16
	v_exp_f32_e32 v179, v179
	v_exp_f32_e32 v180, v180
	v_exp_f32_e32 v224, v224
	v_exp_f32_e32 v226, v226
	v_exp_f32_e32 v227, v227
	v_add_f32_e32 v179, 1.0, v179
	v_add_f32_e32 v178, 1.0, v178
	v_add_f32_e32 v180, 1.0, v180
	v_add_f32_e32 v224, 1.0, v224
	v_rcp_f32_e32 v239, v179
	v_add_f32_e32 v179, 1.0, v226
	v_add_f32_e32 v226, 1.0, v227
	v_rcp_f32_e32 v178, v178
	v_rcp_f32_e32 v180, v180
	v_rcp_f32_e32 v224, v224
	v_rcp_f32_e32 v179, v179
	v_rcp_f32_e32 v226, v226
	v_cvt_pk_bf16_f32 v178, v178, v180
	v_cvt_pk_bf16_f32 v180, v181, v225
	v_cvt_pk_bf16_f32 v179, v224, v179
	v_cvt_pk_bf16_f32 v181, v239, v226
	global_store_dwordx4 v[182:183], v[178:181], off offset:256
	s_nop 1
	v_mul_f32_e32 v179, 0xbfb8aa3b, v10
	v_exp_f32_e32 v179, v179
	v_mul_f32_e32 v180, 0xbfb8aa3b, v19
	v_mul_f32_e32 v181, 0xbfb8aa3b, v11
	v_exp_f32_e32 v180, v180
	v_exp_f32_e32 v181, v181
	v_add_f32_e32 v179, 1.0, v179
	v_rcp_f32_e32 v182, v179
	v_add_f32_e32 v179, 1.0, v180
	v_add_f32_e32 v180, 1.0, v181
	v_mul_f32_e32 v181, 0xbfb8aa3b, v20
	v_mul_f32_e32 v183, 0xbfb8aa3b, v12
	v_mul_f32_e32 v224, 0xbfb8aa3b, v21
	v_mul_f32_e32 v225, 0xbfb8aa3b, v13
	v_exp_f32_e32 v178, v228
	v_exp_f32_e32 v181, v181
	v_exp_f32_e32 v183, v183
	v_exp_f32_e32 v224, v224
	v_exp_f32_e32 v225, v225
	v_add_f32_e32 v178, 1.0, v178
	v_add_f32_e32 v181, 1.0, v181
	v_add_f32_e32 v183, 1.0, v183
	v_add_f32_e32 v224, 1.0, v224
	v_add_f32_e32 v225, 1.0, v225
	v_rcp_f32_e32 v178, v178
	v_rcp_f32_e32 v179, v179
	v_rcp_f32_e32 v180, v180
	v_rcp_f32_e32 v181, v181
	v_rcp_f32_e32 v183, v183
	v_rcp_f32_e32 v224, v224
	v_rcp_f32_e32 v225, v225
	v_add_u32_e32 v0, 0xb0, v0
	v_mad_i64_i32 v[134:135], s[0:1], v0, s47, v[134:135]
	v_cvt_pk_bf16_f32 v178, v178, v179
	v_cvt_pk_bf16_f32 v179, v181, v224
	v_cvt_pk_bf16_f32 v180, v182, v180
	v_cvt_pk_bf16_f32 v181, v183, v225
	v_lshl_add_u64 v[182:183], v[134:135], 0, v[136:137]
	global_store_dwordx4 v[182:183], v[178:181], off
	v_mul_f32_e32 v134, 0xbfb8aa3b, v2
	v_exp_f32_e32 v134, v134
	v_mul_f32_e32 v135, 0xbfb8aa3b, v7
	v_mul_f32_e32 v136, 0xbfb8aa3b, v3
	v_exp_f32_e32 v135, v135
	v_exp_f32_e32 v136, v136
	v_add_f32_e32 v134, 1.0, v134
	v_rcp_f32_e32 v137, v134
	v_add_f32_e32 v134, 1.0, v135
	v_add_f32_e32 v135, 1.0, v136
	v_mul_f32_e32 v136, 0xbfb8aa3b, v8
	v_mul_f32_e32 v178, 0xbfb8aa3b, v4
	v_exp_f32_e32 v136, v136
	v_exp_f32_e32 v178, v178
	v_mul_f32_e32 v0, 0xbfb8aa3b, v6
	v_rcp_f32_e32 v179, v135
	v_add_f32_e32 v135, 1.0, v136
	v_add_f32_e32 v136, 1.0, v178
	v_mul_f32_e32 v178, 0xbfb8aa3b, v9
	v_mul_f32_e32 v180, 0xbfb8aa3b, v5
	v_exp_f32_e32 v0, v0
	v_exp_f32_e32 v178, v178
	v_exp_f32_e32 v180, v180
	v_rcp_f32_e32 v181, v136
	v_add_f32_e32 v0, 1.0, v0
	v_add_f32_e32 v136, 1.0, v178
	v_add_f32_e32 v178, 1.0, v180
	v_rcp_f32_e32 v0, v0
	v_rcp_f32_e32 v134, v134
	v_rcp_f32_e32 v135, v135
	v_rcp_f32_e32 v136, v136
	v_rcp_f32_e32 v178, v178
	v_cvt_pk_bf16_f32 v134, v0, v134
	v_cvt_pk_bf16_f32 v135, v135, v136
	v_cvt_pk_bf16_f32 v136, v137, v179
	v_cvt_pk_bf16_f32 v137, v181, v178
	global_store_dwordx4 v[182:183], v[134:137], off offset:256
	s_mov_b64 s[0:1], 0
